# row-statistics exchange: dropped the agent acquire (slots are written and read with sc1 write-through accesses, nothing else is shared inside the phase)
# speedup vs baseline: 1.0242x; 1.0161x over previous
.LBB0_77:
	s_waitcnt lgkmcnt(0)
.LBB0_78:
	s_waitcnt vmcnt(0) lgkmcnt(0)
	s_barrier
	s_and_saveexec_b64 s[4:5], s[10:11]
	s_cbranch_execz .LBB0_80
	v_readlane_b32 s14, v255, 5
	v_readlane_b32 s15, v255, 6
	s_waitcnt lgkmcnt(0)
	s_nop 0
	v_lshl_add_u64 v[144:145], v[226:227], 4, s[14:15]
	global_load_dword v146, v[144:145], off sc1
	global_load_dword v147, v[144:145], off offset:4 sc1
	global_load_dword v148, v[144:145], off offset:8 sc1
	global_load_dword v149, v[144:145], off offset:12 sc1
	s_waitcnt vmcnt(0)
	v_add_f32_e32 v146, 0, v146
	v_add_f32_e32 v146, v146, v147
	v_add_f32_e32 v146, v146, v148
	v_add_f32_e32 v144, v146, v149
	v_fmamk_f32 v144, v144, 0x3a800000, v236
	v_cmp_gt_f32_e32 vcc, s3, v144
	v_mul_f32_e32 v145, 0x4b800000, v144
	s_nop 0
	v_cndmask_b32_e32 v144, v144, v145, vcc
	v_rsq_f32_e32 v144, v144
	s_nop 0
	v_mul_f32_e32 v145, 0x45800000, v144
	v_cndmask_b32_e32 v144, v144, v145, vcc
	v_lshl_add_u32 v145, v250, 2, 0
	ds_write_b32 v145, v144 offset:4096

.LBB0_111:
	s_waitcnt lgkmcnt(0)
.LBB0_112:
	s_waitcnt vmcnt(0) lgkmcnt(0)
	s_barrier
	s_and_saveexec_b64 s[4:5], s[10:11]
	s_cbranch_execz .LBB0_114
	s_waitcnt lgkmcnt(0)
	v_lshl_add_u64 v[136:137], v[226:227], 4, s[40:41]
	global_load_dword v138, v[136:137], off sc1
	global_load_dword v139, v[136:137], off offset:4 sc1
	global_load_dword v140, v[136:137], off offset:8 sc1
	global_load_dword v141, v[136:137], off offset:12 sc1
	s_waitcnt vmcnt(0)
	v_add_f32_e32 v138, 0, v138
	v_add_f32_e32 v138, v138, v139
	v_add_f32_e32 v138, v138, v140
	v_add_f32_e32 v136, v138, v141
	v_fmamk_f32 v136, v136, 0x3a800000, v236
	v_cmp_gt_f32_e32 vcc, s3, v136
	v_mul_f32_e32 v137, 0x4b800000, v136
	s_nop 0
	v_cndmask_b32_e32 v136, v136, v137, vcc
	v_rsq_f32_e32 v136, v136
	s_nop 0
	v_mul_f32_e32 v137, 0x45800000, v136
	v_cndmask_b32_e32 v136, v136, v137, vcc
	v_lshl_add_u32 v137, v250, 2, 0
	ds_write_b32 v137, v136 offset:4096

.LBB0_165:
	s_waitcnt lgkmcnt(0)
.LBB0_166:
	s_waitcnt vmcnt(0) lgkmcnt(0)
	s_barrier
	s_and_saveexec_b64 s[4:5], s[10:11]
	s_cbranch_execz .LBB0_168
	v_readlane_b32 s14, v255, 5
	v_readlane_b32 s15, v255, 6
	s_waitcnt lgkmcnt(0)
	s_nop 0
	v_lshl_add_u64 v[144:145], v[226:227], 4, s[14:15]
	global_load_dword v146, v[144:145], off sc1
	global_load_dword v147, v[144:145], off offset:4 sc1
	global_load_dword v148, v[144:145], off offset:8 sc1
	global_load_dword v149, v[144:145], off offset:12 sc1
	s_waitcnt vmcnt(0)
	v_add_f32_e32 v146, 0, v146
	v_add_f32_e32 v146, v146, v147
	v_add_f32_e32 v146, v146, v148
	v_add_f32_e32 v144, v146, v149
	v_fmamk_f32 v144, v144, 0x3a800000, v236
	v_cmp_gt_f32_e32 vcc, s3, v144
	v_mul_f32_e32 v145, 0x4b800000, v144
	s_nop 0
	v_cndmask_b32_e32 v144, v144, v145, vcc
	v_rsq_f32_e32 v144, v144
	s_nop 0
	v_mul_f32_e32 v145, 0x45800000, v144
	v_cndmask_b32_e32 v144, v144, v145, vcc
	v_lshl_add_u32 v145, v248, 2, 0
	ds_write_b32 v145, v144 offset:4096

.LBB0_199:
	s_waitcnt lgkmcnt(0)
.LBB0_200:
	s_waitcnt vmcnt(0) lgkmcnt(0)
	s_barrier
	s_and_saveexec_b64 s[4:5], s[10:11]
	s_cbranch_execz .LBB0_202
	s_waitcnt lgkmcnt(0)
	v_lshl_add_u64 v[136:137], v[226:227], 4, s[40:41]
	global_load_dword v138, v[136:137], off sc1
	global_load_dword v139, v[136:137], off offset:4 sc1
	global_load_dword v140, v[136:137], off offset:8 sc1
	global_load_dword v141, v[136:137], off offset:12 sc1
	s_waitcnt vmcnt(0)
	v_add_f32_e32 v138, 0, v138
	v_add_f32_e32 v138, v138, v139
	v_add_f32_e32 v138, v138, v140
	v_add_f32_e32 v136, v138, v141
	v_fmamk_f32 v136, v136, 0x3a800000, v236
	v_cmp_gt_f32_e32 vcc, s3, v136
	v_mul_f32_e32 v137, 0x4b800000, v136
	s_nop 0
	v_cndmask_b32_e32 v136, v136, v137, vcc
	v_rsq_f32_e32 v136, v136
	s_nop 0
	v_mul_f32_e32 v137, 0x45800000, v136
	v_cndmask_b32_e32 v136, v136, v137, vcc
	v_lshl_add_u32 v137, v248, 2, 0
	ds_write_b32 v137, v136 offset:4096
